# prologue rmsnorm rows rotated by 512 waves so the third (partial) row iteration falls on waves with one fewer weight-conversion iteration (tail balance), on top of version 53
# speedup vs baseline: 1.0032x; 1.0032x over previous
.LBB0_17:
	s_cmpk_gt_i32 s9, 0x20ff
	v_mov_b32_e32 v73, 0
	v_lshlrev_b32_e32 v70, 3, v237
	s_cbranch_scc1 .LBB0_77
	v_mbcnt_lo_u32_b32 v1, -1, 0
	v_mbcnt_hi_u32_b32 v2, -1, v1
	v_and_b32_e32 v1, 64, v2
	v_add_u32_e32 v3, 64, v1
	v_xor_b32_e32 v1, 1, v2
	v_cmp_lt_i32_e32 vcc, v1, v3
	v_xor_b32_e32 v4, 2, v2
	s_load_dwordx16 s[12:27], s[0:1], 0x30
	v_cndmask_b32_e32 v1, v2, v1, vcc
	v_cmp_lt_i32_e32 vcc, v4, v3
	v_lshlrev_b32_e32 v72, 4, v237
	s_mov_b64 s[2:3], 0x1000
	v_cndmask_b32_e32 v4, v2, v4, vcc
	v_lshlrev_b32_e32 v92, 2, v4
	v_xor_b32_e32 v4, 4, v2
	v_cmp_lt_i32_e32 vcc, v4, v3
	s_waitcnt lgkmcnt(0)
	v_lshl_add_u64 v[74:75], s[12:13], 0, v[72:73]
	v_lshl_add_u64 v[76:77], v[74:75], 0, s[2:3]
	v_cndmask_b32_e32 v4, v2, v4, vcc
	v_lshlrev_b32_e32 v93, 2, v4
	v_xor_b32_e32 v4, 8, v2
	v_cmp_lt_i32_e32 vcc, v4, v3
	s_mov_b64 s[2:3], 0x1400
	v_lshl_add_u64 v[78:79], v[74:75], 0, s[2:3]
	v_cndmask_b32_e32 v4, v2, v4, vcc
	v_lshlrev_b32_e32 v94, 2, v4
	v_xor_b32_e32 v4, 16, v2
	v_cmp_lt_i32_e32 vcc, v4, v3
	s_mov_b64 s[2:3], 0x1800
	v_lshl_add_u64 v[80:81], v[74:75], 0, s[2:3]
	v_cndmask_b32_e32 v4, v2, v4, vcc
	v_lshlrev_b32_e32 v95, 2, v4
	v_xor_b32_e32 v4, 32, v2
	v_cmp_lt_i32_e32 vcc, v4, v3
	s_mov_b64 s[2:3], 0x1c00
	v_mov_b32_e32 v71, v73
	v_cndmask_b32_e32 v2, v2, v4, vcc
	v_lshl_add_u64 v[82:83], v[74:75], 0, s[2:3]
	v_lshlrev_b32_e32 v96, 2, v2
	v_lshl_add_u64 v[2:3], s[68:69], 0, v[70:71]
	s_mov_b64 s[2:3], 0x8c00000
	s_mov_b32 s7, 0
	v_lshlrev_b32_e32 v1, 2, v1
	v_lshl_add_u64 v[84:85], v[2:3], 0, s[2:3]
	v_mov_b32_e32 v71, 0x358637bd
	s_mov_b32 s20, 0xf800000
	v_mov_b32_e32 v97, 0x260
	s_movk_i32 s21, 0x7fff
	s_mov_b32 s22, 0xffff0000
	v_mov_b32_e32 v98, 1
	s_add_i32 s12, s9, 0x200
	s_cmp_ge_u32 s12, s8
	s_cselect_b32 s6, s8, 0
	s_sub_i32 s12, s12, s6
	global_load_dwordx4 v[150:153], v[74:75], off
	global_load_dwordx4 v[154:157], v[74:75], off offset:1024
	global_load_dwordx4 v[158:161], v[74:75], off offset:2048
	global_load_dwordx4 v[162:165], v[74:75], off offset:3072
	global_load_dwordx4 v[166:169], v[76:77], off
	global_load_dwordx4 v[170:173], v[78:79], off
	global_load_dwordx4 v[174:177], v[80:81], off
	global_load_dwordx4 v[178:181], v[82:83], off
	s_branch .LBB0_20
